# retention phase: static priority raise for waves 4-7 at every item head (all item kinds)
# baseline (speedup 1.0000x reference)
.LBB0_7:
	s_setprio 0
	v_readlane_b32 s0, v252, 62
	s_add_i32 s0, s0, 1
	v_readlane_b32 s52, v253, 3
	v_writelane_b32 v252, s0, 62
	v_readlane_b32 s54, v253, 5
	v_readlane_b32 s56, v253, 7
	v_readlane_b32 s58, v253, 9
	v_readlane_b32 s60, v253, 11
	v_readlane_b32 s62, v253, 13
	v_readlane_b32 s92, v253, 15
	s_waitcnt vmcnt(0) lgkmcnt(0)
	s_barrier
	v_readlane_b32 s53, v253, 4
	v_readlane_b32 s55, v253, 6
	v_readlane_b32 s57, v253, 8
	v_readlane_b32 s59, v253, 10
	v_readlane_b32 s61, v253, 12
	v_readlane_b32 s63, v253, 14
	v_readlane_b32 s93, v253, 16

.LBB0_754:
	v_mov_b32_e32 v0, v192
	s_nop 0
	v_readfirstlane_b32 s0, v0
	s_ashr_i32 s91, s0, 6
	s_and_b32 s12, s91, 3
	s_ashr_i32 s64, s0, 8
	s_cmp_lg_u32 s64, 0
	s_cbranch_scc0 .Lret_item_prio_skip
	s_setprio 1
.Lret_item_prio_skip:
	s_cmpk_gt_i32 s90, 0x1ff
	s_mov_b64 s[0:1], -1
	s_cbranch_scc0 .LBB0_799
	s_cmpk_gt_u32 s90, 0x3ff
	s_cbranch_scc0 .LBB0_759
	s_add_i32 s0, s90, 0xfffffc00
	s_bfe_u32 s26, s90, 0x20002
	s_lshr_b32 s6, s0, 5
	s_lshl_b32 s0, s26, 2
	v_mov_b32_e32 v0, s0
	s_lshl_b32 s0, s90, 7
	s_and_b32 s28, s0, 0x80
	s_lshl_b32 s29, s12, 5
	s_or_b32 s1, s29, s28
	s_bfe_u32 s27, s90, 0x10004
	s_lshl_b32 s1, s1, 9
	s_add_u32 s4, s3, s1
	s_addc_u32 s5, s89, 0
	s_mul_i32 s34, s6, 0x300000
	v_readlane_b32 s8, v254, 39
	s_mul_hi_u32 s31, s6, 0x300000
	v_readlane_b32 s9, v254, 40
	s_add_u32 s1, s8, s34
	s_addc_u32 s20, s9, s31
	s_lshl_b32 s35, s26, 9
	s_mov_b32 s7, s96
	s_add_u32 s24, s1, s35
	s_addc_u32 s25, s20, 0
	s_lshl_b64 s[20:21], s[6:7], 11
	s_or_b32 s1, s20, s35
	s_and_b32 s0, s0, 0x100
	v_readlane_b32 s44, v254, 43
	s_or_b32 s20, s1, s0
	v_readlane_b32 s58, v254, 57
	v_readlane_b32 s59, v254, 58
	s_lshl_b64 s[20:21], s[20:21], 9
	v_readlane_b32 s8, v254, 37
	v_mov_b32_e32 v10, v192
	s_nop 1
	global_load_dword v8, v0, s[58:59]
	global_load_dword v9, v0, s[58:59] offset:16
	v_readlane_b32 s9, v254, 38
	s_add_u32 s22, s8, s20
	s_addc_u32 s23, s9, s21
	v_and_b32_e32 v113, 31, v10
	v_readfirstlane_b32 s1, v10
	v_bfe_u32 v12, v10, 5, 1
	v_lshlrev_b32_e32 v146, 9, v113
	v_mov_b32_e32 v147, v112
	s_ashr_i32 s36, s1, 6
	v_lshl_add_u64 v[0:1], s[4:5], 0, v[146:147]
	v_lshlrev_b32_e32 v2, 4, v12
	v_mov_b32_e32 v3, v112
	s_lshl_b32 s4, s36, 3
	v_lshl_add_u64 v[0:1], v[0:1], 0, v[2:3]
	v_bitop3_b32 v2, s4, v10, v12 bitop3:0x36
	v_lshlrev_b32_e32 v2, 3, v2
	global_load_dwordx4 v[142:145], v[0:1], off
	global_load_dwordx4 v[138:141], v[0:1], off offset:32
	global_load_dwordx4 v[134:137], v[0:1], off offset:64
	global_load_dwordx4 v[130:133], v[0:1], off offset:96
	global_load_dwordx4 v[126:129], v[0:1], off offset:128
	global_load_dwordx4 v[122:125], v[0:1], off offset:160
	global_load_dwordx4 v[118:121], v[0:1], off offset:192
	global_load_dwordx4 v[114:117], v[0:1], off offset:224
	global_load_dwordx4 v[108:111], v[0:1], off offset:256
	global_load_dwordx4 v[104:107], v[0:1], off offset:288
	global_load_dwordx4 v[100:103], v[0:1], off offset:320
	global_load_dwordx4 v[96:99], v[0:1], off offset:352
	global_load_dwordx4 v[92:95], v[0:1], off offset:384
	global_load_dwordx4 v[88:91], v[0:1], off offset:416
	global_load_dwordx4 v[84:87], v[0:1], off offset:448
	global_load_dwordx4 v[80:83], v[0:1], off offset:480
	s_lshl_b32 s1, s36, 2
	v_or_b32_e32 v0, s4, v12
	v_and_b32_e32 v13, 0xf8, v2
	v_lshlrev_b32_e32 v2, 4, v10
	v_and_b32_e32 v3, 48, v10
	s_movk_i32 s4, 0x70
	v_bitop3_b32 v16, v2, v3, s4 bitop3:0x6c
	s_or_b32 s4, s1, 1
	s_lshl_b32 s5, s4, 1
	v_bitop3_b32 v3, s5, v10, v12 bitop3:0x36
	v_bfe_u32 v1, v10, 3, 3
	v_lshlrev_b32_e32 v3, 3, v3
	v_and_b32_e32 v18, 0xf8, v3
	v_lshl_or_b32 v3, s4, 3, v1
	v_lshrrev_b32_e32 v4, 1, v3
	v_xor_b32_e32 v4, v4, v10
	s_or_b32 s4, s1, 2
	v_or_b32_e32 v2, s5, v12
	v_lshlrev_b32_e32 v4, 4, v4
	s_lshl_b32 s5, s4, 1
	v_and_b32_e32 v19, 0x70, v4
	v_bitop3_b32 v4, s5, v10, v12 bitop3:0x36
	s_movk_i32 s59, 0x1800
	v_lshl_or_b32 v20, v3, 9, v19
	v_or_b32_e32 v3, s5, v12
	v_lshlrev_b32_e32 v4, 3, v4
	v_mul_lo_u32 v3, v3, s59
	v_and_b32_e32 v21, 0xf8, v4
	v_or_b32_e32 v3, v21, v3
	v_lshlrev_b32_e32 v4, 1, v3
	v_lshl_or_b32 v3, s4, 3, v1
	v_lshrrev_b32_e32 v5, 1, v3
	v_xor_b32_e32 v5, v5, v10
	s_or_b32 s1, s1, 3
	v_lshlrev_b32_e32 v5, 4, v5
	s_lshl_b32 s4, s1, 1
	v_and_b32_e32 v22, 0x70, v5
	v_bitop3_b32 v5, s4, v10, v12 bitop3:0x36
	v_lshl_or_b32 v23, v3, 9, v22
	v_or_b32_e32 v3, s4, v12
	v_lshlrev_b32_e32 v5, 3, v5
	v_mul_lo_u32 v3, v3, s59
	v_and_b32_e32 v24, 0xf8, v5
	v_lshlrev_b32_e32 v14, 9, v1
	v_or_b32_e32 v3, v24, v3
	v_lshl_or_b32 v1, s1, 3, v1
	v_lshlrev_b32_e32 v6, 1, v3
	v_lshrrev_b32_e32 v3, 1, v1
	v_xor_b32_e32 v3, v3, v10
	v_mul_lo_u32 v0, v0, s59
	v_lshlrev_b32_e32 v3, 4, v3
	v_or_b32_e32 v0, v13, v0
	v_and_b32_e32 v25, 0x70, v3
	v_lshlrev_b32_e32 v0, 1, v0
	v_mul_lo_u32 v2, v2, s59
	v_lshl_or_b32 v26, v1, 9, v25
	v_mov_b32_e32 v1, v112
	s_lshl_b32 s1, s36, 12
	v_or_b32_e32 v2, v18, v2
	v_lshl_add_u64 v[0:1], s[24:25], 0, v[0:1]
	s_mov_b64 s[4:5], 0x800
	s_add_i32 s7, s1, 0
	v_lshlrev_b32_e32 v2, 1, v2
	v_lshl_add_u64 v[0:1], v[0:1], 0, s[4:5]
	s_mov_b32 m0, s7
	v_mov_b32_e32 v3, v112
	global_load_lds_dwordx4 v[0:1], off
	v_lshl_add_u64 v[0:1], s[24:25], 0, v[2:3]
	v_lshl_add_u64 v[0:1], v[0:1], 0, s[4:5]
	s_add_i32 m0, s7, 0x400
	v_mov_b32_e32 v5, v112
	global_load_lds_dwordx4 v[0:1], off
	v_lshl_add_u64 v[0:1], s[24:25], 0, v[4:5]
	v_lshl_add_u64 v[0:1], v[0:1], 0, s[4:5]
	s_add_i32 m0, s7, 0x800
	v_mov_b32_e32 v7, v112
	s_lshl_b32 s37, s36, 14
	global_load_lds_dwordx4 v[0:1], off
	v_lshl_add_u64 v[0:1], s[24:25], 0, v[6:7]
	v_or_b32_e32 v15, s37, v14
	v_lshl_add_u64 v[0:1], v[0:1], 0, s[4:5]
	s_add_i32 m0, s7, 0xc00
	v_or_b32_e32 v17, v15, v16
	global_load_lds_dwordx4 v[0:1], off
	s_add_i32 m0, s7, 0x8000
	s_lshl_b32 s1, s36, 11
	global_load_lds_dwordx4 v17, s[22:23]
	s_add_i32 m0, s7, 0x8400
	s_add_i32 s25, 0, 0x20000
	global_load_lds_dwordx4 v20, s[22:23]
	s_add_i32 m0, s7, 0x8800
	s_add_i32 s24, s25, s1
	global_load_lds_dwordx4 v23, s[22:23]
	s_add_i32 m0, s7, 0x8c00
	s_xor_b32 s1, s1, 0x2000
	global_load_lds_dwordx4 v26, s[22:23]
	s_add_i32 s25, s25, s1
	s_lshl_b32 s23, s64, 14
	s_lshl_b32 s58, s64, 5
	v_bitop3_b32 v0, v12, v10, 31 bitop3:0x78
	s_cmp_eq_u32 s27, 0
	v_lshlrev_b32_e32 v175, 4, v0
	v_lshrrev_b32_e32 v0, 1, v10
	s_cselect_b64 vcc, -1, 0
	s_lshl_b32 s22, s64, 6
	v_lshlrev_b32_e32 v147, 2, v12
	v_bitop3_b32 v0, v0, v12, 7 bitop3:0x6c
	s_or_b32 s5, s22, 32
	s_sub_i32 s4, 64, s22
	s_sub_i32 s1, 0x60, s22
	s_add_i32 s23, s23, 0
	v_lshlrev_b32_e32 v172, 4, v0
	s_waitcnt vmcnt(0)
	v_cndmask_b32_e32 v0, v9, v8, vcc
	s_mov_b32 s60, 0xbfb8aa3b
	v_or_b32_e32 v174, s58, v147
	s_add_u32 s20, s20, 0x2800080
	s_movk_i32 s58, 0x3000
	v_mul_f32_e64 v173, |v0|, s60
	s_addc_u32 s21, s21, 0
	v_or3_b32 v0, v15, v25, s58
	v_mov_b32_e32 v1, v112
	s_movk_i32 s58, 0x2000
	v_lshl_add_u64 v[148:149], s[20:21], 0, v[0:1]
	v_or3_b32 v0, v15, v22, s58
	s_movk_i32 s8, 0x1000
	v_lshl_add_u64 v[150:151], s[20:21], 0, v[0:1]
	v_or3_b32 v0, v15, v19, s8
	v_lshl_add_u64 v[152:153], s[20:21], 0, v[0:1]
	v_or3_b32 v0, v16, s37, v14
	v_lshl_add_u64 v[154:155], s[20:21], 0, v[0:1]
	s_or_b32 s20, s34, s35
	s_add_u32 s20, s20, 0x48c0800
	s_addc_u32 s21, s31, 0
	s_mul_i32 s31, s36, 0xc000
	s_add_i32 s34, s31, 0x9000
	v_mov_b32_e32 v0, s34
	v_mad_u32_u24 v0, v12, s59, v0
	v_or_b32_e32 v0, v0, v24
	v_mul_u32_u24_e32 v2, 0x1800, v12
	v_lshlrev_b32_e32 v0, 1, v0
	s_add_i32 s34, s31, 0x6000
	v_lshl_add_u64 v[156:157], s[20:21], 0, v[0:1]
	v_or3_b32 v0, s34, v2, v21
	v_lshlrev_b32_e32 v0, 1, v0
	v_or_b32_e32 v2, s31, v2
	v_lshl_add_u64 v[158:159], s[20:21], 0, v[0:1]
	v_or_b32_e32 v0, v2, v18
	v_lshl_add_u32 v0, v0, 1, v206
	v_lshl_add_u64 v[160:161], s[20:21], 0, v[0:1]
	v_or_b32_e32 v0, v2, v13
	s_waitcnt vmcnt(0)
	v_lshlrev_b32_e32 v0, 1, v0
	v_and_b32_e32 v11, 63, v10
	v_lshl_add_u64 v[170:171], s[20:21], 0, v[0:1]
	v_mov_b32_e32 v0, 0
	v_lshlrev_b32_e32 v176, 4, v11
	v_lshlrev_b32_e32 v162, 7, v113
	s_mov_b32 s30, 0
	v_sub_u32_e32 v177, 0xff, v174
	s_mov_b32 s20, 0
	v_mov_b32_e32 v1, v0
	v_mov_b32_e32 v2, v0
	v_mov_b32_e32 v3, v0
	v_mov_b32_e32 v4, v0
	v_mov_b32_e32 v5, v0
	v_mov_b32_e32 v6, v0
	v_mov_b32_e32 v7, v0
	v_mov_b32_e32 v8, v0
	v_mov_b32_e32 v9, v0
	v_mov_b32_e32 v10, v0
	v_mov_b32_e32 v11, v0
	v_mov_b32_e32 v12, v0
	v_mov_b32_e32 v13, v0
	v_mov_b32_e32 v14, v0
	v_mov_b32_e32 v15, v0
	v_mov_b32_e32 v48, v0
	v_mov_b32_e32 v49, v0
	v_mov_b32_e32 v50, v0
	v_mov_b32_e32 v51, v0
	v_mov_b32_e32 v52, v0
	v_mov_b32_e32 v53, v0
	v_mov_b32_e32 v54, v0
	v_mov_b32_e32 v55, v0
	v_mov_b32_e32 v56, v0
	v_mov_b32_e32 v57, v0
	v_mov_b32_e32 v58, v0
	v_mov_b32_e32 v59, v0
	v_mov_b32_e32 v60, v0
	v_mov_b32_e32 v61, v0
	v_mov_b32_e32 v62, v0
	v_mov_b32_e32 v63, v0
	v_mov_b32_e32 v32, v0
	v_mov_b32_e32 v33, v0
	v_mov_b32_e32 v34, v0
	v_mov_b32_e32 v35, v0
	v_mov_b32_e32 v36, v0
	v_mov_b32_e32 v37, v0
	v_mov_b32_e32 v38, v0
	v_mov_b32_e32 v39, v0
	v_mov_b32_e32 v40, v0
	v_mov_b32_e32 v41, v0
	v_mov_b32_e32 v42, v0
	v_mov_b32_e32 v43, v0
	v_mov_b32_e32 v44, v0
	v_mov_b32_e32 v45, v0
	v_mov_b32_e32 v46, v0
	v_mov_b32_e32 v47, v0
	v_mov_b32_e32 v16, v0
	v_mov_b32_e32 v17, v0
	v_mov_b32_e32 v18, v0
	v_mov_b32_e32 v19, v0
	v_mov_b32_e32 v20, v0
	v_mov_b32_e32 v21, v0
	v_mov_b32_e32 v22, v0
	v_mov_b32_e32 v23, v0
	v_mov_b32_e32 v24, v0
	v_mov_b32_e32 v25, v0
	v_mov_b32_e32 v26, v0
	v_mov_b32_e32 v27, v0
	v_mov_b32_e32 v28, v0
	v_mov_b32_e32 v29, v0
	v_mov_b32_e32 v30, v0
	v_mov_b32_e32 v31, v0
	s_mov_b32 s34, 0x8000
	s_mov_b64 s[36:37], 0xc0000
	s_mov_b32 s58, 0x3d800000
	v_readlane_b32 s45, v254, 44
	v_readlane_b32 s46, v254, 45
	v_readlane_b32 s47, v254, 46
	v_readlane_b32 s48, v254, 47
	v_readlane_b32 s49, v254, 48
	v_readlane_b32 s50, v254, 49
	v_readlane_b32 s51, v254, 50
	v_readlane_b32 s52, v254, 51
	v_readlane_b32 s53, v254, 52
	v_readlane_b32 s54, v254, 53
	v_readlane_b32 s55, v254, 54
	v_readlane_b32 s56, v254, 55
	v_readlane_b32 s57, v254, 56
	s_waitcnt lgkmcnt(0)
	s_barrier
